# bundle: v28 + redundant post-barrier lgkmcnt removed + RWKV producer sqrt/rcp + P12 K-row loads all issued before the first dot products
# baseline (speedup 1.0000x reference)
; __device__ __forceinline__ f32x4 unpack4(u32x2 u) { return (f32x4){__uint_as_float(u.x << 16), __uint_as_float(u.x & 0xffff0000u), __uint_as_float(u.y << 16), __uint_as_float(u.y & 0xffff0000u)}; }
; __device__ __forceinline__ float dot4(f32x4 a, f32x4 b) { return (a.x * b.x + a.y * b.y) + (a.z * b.z + a.w * b.w); }
; template <int ph>
; __device__ __forceinline__ void run_phase(const Args& args, LAS unsigned char* lds, const int G, const int bx, const bool fin = true) {
;     ...
;             const f32x4 q = unpack4(*(const u32x2*)(QB + (size_t)(MP + i) * D + h * 256 + 4 * lane));
;             const float* kb = cache_k + ((size_t)i * 256 * 4 + h) * 256 + 4 * lane + (size_t)(wave * 32) * 1024;
;             const float* vb = cache_v + ((size_t)i * 256 * 4 + h) * 256 + 4 * lane + (size_t)(wave * 32) * 1024;
;             f32x4 kx[32];
; #pragma unroll
;             for (int mm = 0; mm < 32; ++mm) kx[mm] = __builtin_nontemporal_load((const f32x4*)(kb + (size_t)mm * 1024));
; #pragma unroll
;             for (int mm = 0; mm < 32; ++mm) sT[mm * 66 + lane] = dot4(q, kx[mm]);
.LBB0_1511:
	s_ashr_i32 s6, s39, 2
	s_add_i32 s0, s6, 0x4000
	s_ashr_i32 s1, s0, 31
	s_lshl_b64 s[8:9], s[0:1], 11
	s_add_u32 s7, s10, s8
	s_addc_u32 s9, s11, s9
	s_lshl_b32 s8, s39, 8
	s_and_b32 s41, s8, 0x300
	s_lshl_b32 s40, s41, 1
	s_add_u32 s8, s7, s40
	s_addc_u32 s9, s9, 0
	s_ashr_i32 s7, s6, 31
	global_load_dwordx2 v[150:151], v139, s[8:9]
	s_lshl_b64 s[8:9], s[6:7], 18
	s_or_b32 s8, s8, s41
	v_lshl_add_u64 v[124:125], s[8:9], 2, v[130:131]
	global_load_dwordx4 v[0:3], v[124:125], off nt
	v_add_co_u32_e32 v8, vcc, s17, v124
	s_nop 1
	v_addc_co_u32_e32 v9, vcc, 0, v125, vcc
	global_load_dwordx4 v[4:7], v[8:9], off offset:-4096 nt
	v_add_co_u32_e32 v16, vcc, s16, v124
	s_nop 0
	s_nop 0
	v_addc_co_u32_e32 v17, vcc, 0, v125, vcc
	global_load_dwordx4 v[12:15], v[16:17], off offset:-4096 nt
	v_add_co_u32_e32 v24, vcc, s18, v124
	global_load_dwordx4 v[8:11], v[8:9], off nt
	s_nop 0
	v_addc_co_u32_e32 v25, vcc, 0, v125, vcc
	global_load_dwordx4 v[16:19], v[16:17], off nt
	v_add_co_u32_e32 v84, vcc, s19, v124
	global_load_dwordx4 v[20:23], v[24:25], off offset:-4096 nt
	s_nop 0
	v_addc_co_u32_e32 v85, vcc, 0, v125, vcc
	global_load_dwordx4 v[24:27], v[24:25], off nt
	v_add_co_u32_e32 v86, vcc, s20, v124
	s_nop 0
	s_nop 0
	v_addc_co_u32_e32 v87, vcc, 0, v125, vcc
	v_add_co_u32_e32 v88, vcc, s21, v124
	s_nop 0
	s_nop 0
	v_addc_co_u32_e32 v89, vcc, 0, v125, vcc
	v_add_co_u32_e32 v90, vcc, s22, v124
	s_nop 0
	s_nop 0
	v_addc_co_u32_e32 v91, vcc, 0, v125, vcc
	v_add_co_u32_e32 v92, vcc, s23, v124
	s_nop 0
	s_nop 0
	v_addc_co_u32_e32 v93, vcc, 0, v125, vcc
	v_add_co_u32_e32 v94, vcc, s24, v124
	s_nop 0
	s_nop 0
	v_addc_co_u32_e32 v95, vcc, 0, v125, vcc
	v_add_co_u32_e32 v96, vcc, s25, v124
	s_nop 0
	s_nop 0
	v_addc_co_u32_e32 v97, vcc, 0, v125, vcc
	v_add_co_u32_e32 v98, vcc, s26, v124
	s_nop 0
	s_nop 0
	v_addc_co_u32_e32 v99, vcc, 0, v125, vcc
	v_add_co_u32_e32 v100, vcc, s27, v124
	s_nop 1
	v_addc_co_u32_e32 v101, vcc, 0, v125, vcc
	global_load_dwordx4 v[28:31], v[84:85], off offset:-4096 nt
	global_load_dwordx4 v[32:35], v[84:85], off nt
	global_load_dwordx4 v[36:39], v[86:87], off offset:-4096 nt
	global_load_dwordx4 v[40:43], v[86:87], off nt
	global_load_dwordx4 v[44:47], v[88:89], off offset:-4096 nt
	global_load_dwordx4 v[48:51], v[88:89], off nt
	global_load_dwordx4 v[52:55], v[90:91], off offset:-4096 nt
	global_load_dwordx4 v[56:59], v[90:91], off nt
	global_load_dwordx4 v[60:63], v[92:93], off offset:-4096 nt
	global_load_dwordx4 v[64:67], v[92:93], off nt
	global_load_dwordx4 v[68:71], v[94:95], off offset:-4096 nt
	global_load_dwordx4 v[72:75], v[94:95], off nt
	global_load_dwordx4 v[76:79], v[96:97], off offset:-4096 nt
	global_load_dwordx4 v[80:83], v[96:97], off nt
	global_load_dwordx4 v[84:87], v[98:99], off offset:-4096 nt
	global_load_dwordx4 v[88:91], v[98:99], off nt
	s_nop 0
	global_load_dwordx4 v[92:95], v[100:101], off offset:-4096 nt
	global_load_dwordx4 v[96:99], v[100:101], off nt
	v_add_co_u32_e32 v104, vcc, s28, v124
	s_nop 0
	s_nop 0
	v_addc_co_u32_e32 v105, vcc, 0, v125, vcc
	global_load_dwordx4 v[100:103], v[104:105], off offset:-4096 nt
	s_nop 0
	global_load_dwordx4 v[104:107], v[104:105], off nt
	v_add_co_u32_e32 v112, vcc, s29, v124
	s_nop 0
	s_nop 0
	v_addc_co_u32_e32 v113, vcc, 0, v125, vcc
	global_load_dwordx4 v[108:111], v[112:113], off offset:-4096 nt
	s_nop 0
	global_load_dwordx4 v[112:115], v[112:113], off nt
	v_add_co_u32_e32 v120, vcc, s36, v124
	s_nop 0
	s_nop 0
	v_addc_co_u32_e32 v121, vcc, 0, v125, vcc
	global_load_dwordx4 v[116:119], v[120:121], off offset:-4096 nt
	s_nop 0
	global_load_dwordx4 v[120:123], v[120:121], off nt
	v_add_co_u32_e32 v124, vcc, s37, v124
	s_nop 0
	s_nop 0
	v_addc_co_u32_e32 v125, vcc, 0, v125, vcc
	global_load_dwordx4 v[124:127], v[124:125], off nt
	s_waitcnt vmcnt(31)
	v_lshlrev_b32_e32 v149, 16, v150
	v_and_b32_e32 v150, 0xffff0000, v150
	v_lshlrev_b32_e32 v152, 16, v151
	v_and_b32_e32 v151, 0xffff0000, v151
	v_mul_f32_e32 v1, v1, v150
	v_fmac_f32_e32 v1, v0, v149
	v_mul_f32_e32 v0, v3, v151
	v_fmac_f32_e32 v0, v2, v152
	v_add_f32_e32 v0, v1, v0
	s_waitcnt vmcnt(30)
	v_mul_f32_e32 v1, v5, v150
	v_mul_f32_e32 v2, v7, v151
	v_fmac_f32_e32 v1, v4, v149
	v_fmac_f32_e32 v2, v6, v152
	v_add_f32_e32 v1, v1, v2
	ds_write2_b32 v140, v0, v1 offset1:66
	s_waitcnt vmcnt(28)
	v_mul_f32_e32 v0, v9, v150
	v_mul_f32_e32 v1, v11, v151
	v_fmac_f32_e32 v0, v8, v149
	v_fmac_f32_e32 v1, v10, v152
	v_add_f32_e32 v0, v0, v1
	v_mul_f32_e32 v1, v13, v150
	v_mul_f32_e32 v2, v15, v151
	v_fmac_f32_e32 v1, v12, v149
	v_fmac_f32_e32 v2, v14, v152
	v_add_f32_e32 v1, v1, v2
	ds_write2_b32 v140, v0, v1 offset0:132 offset1:198
	s_waitcnt vmcnt(27)
	v_mul_f32_e32 v0, v17, v150
	v_mul_f32_e32 v1, v19, v151
	v_fmac_f32_e32 v0, v16, v149
	v_fmac_f32_e32 v1, v18, v152
	v_add_f32_e32 v0, v0, v1
	s_waitcnt vmcnt(26)
	v_mul_f32_e32 v1, v21, v150
	v_mul_f32_e32 v2, v23, v151
	v_fmac_f32_e32 v1, v20, v149
	v_fmac_f32_e32 v2, v22, v152
	v_add_f32_e32 v1, v1, v2
	ds_write2_b32 v141, v0, v1 offset0:8 offset1:74
	s_waitcnt vmcnt(25)
; __device__ __forceinline__ float dot4(f32x4 a, f32x4 b) { return (a.x * b.x + a.y * b.y) + (a.z * b.z + a.w * b.w); }
; template <int ph>
; __device__ __forceinline__ void run_phase(const Args& args, LAS unsigned char* lds, const int G, const int bx, const bool fin = true) {
;     ...
;             for (int mm = 0; mm < 32; ++mm) kx[mm] = __builtin_nontemporal_load((const f32x4*)(kb + (size_t)mm * 1024));
; #pragma unroll
;             for (int mm = 0; mm < 32; ++mm) sT[mm * 66 + lane] = dot4(q, kx[mm]);
;             asm volatile("s_waitcnt lgkmcnt(0)" ::: "memory");
;             if (lane < 32) { float s = 0.f;
	v_mul_f32_e32 v0, v25, v150
	v_mul_f32_e32 v1, v27, v151
	v_fmac_f32_e32 v0, v24, v149
	v_fmac_f32_e32 v1, v26, v152
	v_add_f32_e32 v0, v0, v1
	s_waitcnt vmcnt(24)
	v_mul_f32_e32 v1, v29, v150
	v_mul_f32_e32 v2, v31, v151
	v_fmac_f32_e32 v1, v28, v149
	v_fmac_f32_e32 v2, v30, v152
	v_add_f32_e32 v1, v1, v2
	ds_write2_b32 v141, v0, v1 offset0:140 offset1:206
	s_waitcnt vmcnt(23)
	v_mul_f32_e32 v0, v33, v150
	v_mul_f32_e32 v1, v35, v151
	v_fmac_f32_e32 v0, v32, v149
	v_fmac_f32_e32 v1, v34, v152
	v_add_f32_e32 v0, v0, v1
	s_waitcnt vmcnt(22)
	v_mul_f32_e32 v1, v37, v150
	v_mul_f32_e32 v2, v39, v151
	v_fmac_f32_e32 v1, v36, v149
	v_fmac_f32_e32 v2, v38, v152
	v_add_f32_e32 v1, v1, v2
	ds_write2_b32 v142, v0, v1 offset0:16 offset1:82
	s_waitcnt vmcnt(21)
	v_mul_f32_e32 v0, v41, v150
	v_mul_f32_e32 v1, v43, v151
	v_fmac_f32_e32 v0, v40, v149
	v_fmac_f32_e32 v1, v42, v152
	v_add_f32_e32 v0, v0, v1
	s_waitcnt vmcnt(20)
	v_mul_f32_e32 v1, v45, v150
	v_mul_f32_e32 v2, v47, v151
	v_fmac_f32_e32 v1, v44, v149
	v_fmac_f32_e32 v2, v46, v152
	v_add_f32_e32 v1, v1, v2
	ds_write2_b32 v142, v0, v1 offset0:148 offset1:214
	s_waitcnt vmcnt(19)
	v_mul_f32_e32 v0, v49, v150
	v_mul_f32_e32 v1, v51, v151
	v_fmac_f32_e32 v0, v48, v149
	v_fmac_f32_e32 v1, v50, v152
	v_add_f32_e32 v0, v0, v1
	s_waitcnt vmcnt(18)
	v_mul_f32_e32 v1, v53, v150
	v_mul_f32_e32 v2, v55, v151
	v_fmac_f32_e32 v1, v52, v149
	v_fmac_f32_e32 v2, v54, v152
	v_add_f32_e32 v1, v1, v2
	ds_write2_b32 v143, v0, v1 offset0:24 offset1:90
	s_waitcnt vmcnt(17)
	v_mul_f32_e32 v0, v57, v150
	v_mul_f32_e32 v1, v59, v151
	v_fmac_f32_e32 v0, v56, v149
	v_fmac_f32_e32 v1, v58, v152
	v_add_f32_e32 v0, v0, v1
	s_waitcnt vmcnt(16)
	v_mul_f32_e32 v1, v61, v150
	v_mul_f32_e32 v2, v63, v151
	v_fmac_f32_e32 v1, v60, v149
	v_fmac_f32_e32 v2, v62, v152
	v_add_f32_e32 v1, v1, v2
	ds_write2_b32 v143, v0, v1 offset0:156 offset1:222
	s_waitcnt vmcnt(15)
	v_mul_f32_e32 v0, v65, v150
	v_mul_f32_e32 v1, v67, v151
	v_fmac_f32_e32 v0, v64, v149
	v_fmac_f32_e32 v1, v66, v152
	v_add_f32_e32 v0, v0, v1
	s_waitcnt vmcnt(14)
	v_mul_f32_e32 v1, v69, v150
	v_mul_f32_e32 v2, v71, v151
	v_fmac_f32_e32 v1, v68, v149
	v_fmac_f32_e32 v2, v70, v152
	v_add_f32_e32 v1, v1, v2
	ds_write2_b32 v144, v0, v1 offset0:32 offset1:98
	s_waitcnt vmcnt(13)
	v_mul_f32_e32 v0, v73, v150
	v_mul_f32_e32 v1, v75, v151
	v_fmac_f32_e32 v0, v72, v149
	v_fmac_f32_e32 v1, v74, v152
	v_add_f32_e32 v0, v0, v1
	s_waitcnt vmcnt(12)
	v_mul_f32_e32 v1, v77, v150
	v_mul_f32_e32 v2, v79, v151
	v_fmac_f32_e32 v1, v76, v149
	v_fmac_f32_e32 v2, v78, v152
	v_add_f32_e32 v1, v1, v2
	ds_write2_b32 v144, v0, v1 offset0:164 offset1:230
	s_waitcnt vmcnt(11)
	v_mul_f32_e32 v0, v81, v150
	v_mul_f32_e32 v1, v83, v151
	v_fmac_f32_e32 v0, v80, v149
	v_fmac_f32_e32 v1, v82, v152
	v_add_f32_e32 v0, v0, v1
	s_waitcnt vmcnt(10)
	v_mul_f32_e32 v1, v85, v150
	v_mul_f32_e32 v2, v87, v151
	v_fmac_f32_e32 v1, v84, v149
	v_fmac_f32_e32 v2, v86, v152
	v_add_f32_e32 v1, v1, v2
	ds_write2_b32 v145, v0, v1 offset0:40 offset1:106
	s_waitcnt vmcnt(9)
	v_mul_f32_e32 v0, v89, v150
	v_mul_f32_e32 v1, v91, v151
	v_fmac_f32_e32 v0, v88, v149
	v_fmac_f32_e32 v1, v90, v152
	v_add_f32_e32 v0, v0, v1
	s_waitcnt vmcnt(8)
	v_mul_f32_e32 v1, v93, v150
	v_mul_f32_e32 v2, v95, v151
	v_fmac_f32_e32 v1, v92, v149
	v_fmac_f32_e32 v2, v94, v152
	v_add_f32_e32 v1, v1, v2
	ds_write2_b32 v145, v0, v1 offset0:172 offset1:238
	s_waitcnt vmcnt(7)
	v_mul_f32_e32 v0, v97, v150
	v_mul_f32_e32 v1, v99, v151
	v_fmac_f32_e32 v0, v96, v149
	v_fmac_f32_e32 v1, v98, v152
	v_add_f32_e32 v0, v0, v1
	s_waitcnt vmcnt(6)
	v_mul_f32_e32 v1, v101, v150
	v_mul_f32_e32 v2, v103, v151
	v_fmac_f32_e32 v1, v100, v149
	v_fmac_f32_e32 v2, v102, v152
	v_add_f32_e32 v1, v1, v2
	ds_write2_b32 v146, v0, v1 offset0:48 offset1:114
	s_waitcnt vmcnt(5)
	v_mul_f32_e32 v0, v105, v150
	v_mul_f32_e32 v1, v107, v151
	v_fmac_f32_e32 v0, v104, v149
	v_fmac_f32_e32 v1, v106, v152
	v_add_f32_e32 v0, v0, v1
	s_waitcnt vmcnt(4)
	v_mul_f32_e32 v1, v109, v150
	v_mul_f32_e32 v2, v111, v151
	v_fmac_f32_e32 v1, v108, v149
	v_fmac_f32_e32 v2, v110, v152
	v_add_f32_e32 v1, v1, v2
	ds_write2_b32 v146, v0, v1 offset0:180 offset1:246
	s_waitcnt vmcnt(3)
	v_mul_f32_e32 v0, v113, v150
	v_mul_f32_e32 v1, v115, v151
	v_fmac_f32_e32 v0, v112, v149
	v_fmac_f32_e32 v1, v114, v152
	v_add_f32_e32 v0, v0, v1
	s_waitcnt vmcnt(2)
	v_mul_f32_e32 v1, v117, v150
	v_mul_f32_e32 v2, v119, v151
	v_fmac_f32_e32 v1, v116, v149
	v_fmac_f32_e32 v2, v118, v152
	v_add_f32_e32 v1, v1, v2
	ds_write2_b32 v147, v0, v1 offset0:56 offset1:122
	s_waitcnt vmcnt(1)
	v_mul_f32_e32 v0, v121, v150
	v_mul_f32_e32 v1, v123, v151
	v_fmac_f32_e32 v0, v120, v149
	v_fmac_f32_e32 v1, v122, v152
	v_add_f32_e32 v0, v0, v1
	s_waitcnt vmcnt(0)
	v_mul_f32_e32 v1, v125, v150
	v_mul_f32_e32 v2, v127, v151
	v_fmac_f32_e32 v1, v124, v149
	v_fmac_f32_e32 v2, v126, v152
	v_add_f32_e32 v1, v1, v2
	ds_write2_b32 v147, v0, v1 offset0:188 offset1:254
	s_waitcnt lgkmcnt(0)
	s_and_saveexec_b64 s[6:7], s[2:3]
	s_cbranch_execz .LBB0_1515
	v_mov_b32_e32 v0, 0
	s_mov_b32 s41, 0
